# XCD-local barrier: waiters poll the arrival counter directly (target 32*(gen+1)) instead of a generation word bumped by the last arriver
# speedup vs baseline: 1.0322x; 1.0101x over previous
.LBB0_570:
	s_or_b64 exec, exec, s[8:9]
	s_waitcnt vmcnt(0)
	v_readfirstlane_b32 s8, v1
	s_mov_b64 s[34:35], -1
	s_nop 0
	v_add_u32_e32 v2, s8, v0
	v_readlane_b32 s8, v234, 36
	v_and_b32_e32 v0, 31, v2
	v_readlane_b32 s9, v234, 37
	v_cmp_ne_u32_e32 vcc, 31, v0
	s_nop 0
	v_mov_b64_e32 v[0:1], s[8:9]
	s_and_saveexec_b64 s[8:9], vcc
	s_cbranch_execz .LBB0_582
	v_readlane_b32 s34, v234, 34
	v_readlane_b32 s35, v234, 35
	v_or_b32_e32 v0, 31, v2
	v_add_u32_e32 v0, 1, v0
	s_mov_b64 s[38:39], 0
	s_nop 2
	global_load_dword v1, v97, s[34:35] sc1
	s_waitcnt vmcnt(0)
	v_cmp_lt_u32_e32 vcc, v1, v0
	s_and_saveexec_b64 s[34:35], vcc
	s_cbranch_execz .LBB0_581
	s_mov_b32 s46, 1
	s_branch .LBB0_574

.LBB0_576:
	v_readlane_b32 s42, v234, 34
	v_readlane_b32 s43, v234, 35
	s_add_i32 s46, s46, 1
	s_mov_b64 s[72:73], -1
	s_nop 2
	global_load_dword v1, v97, s[42:43] sc1
	s_waitcnt vmcnt(0)
	v_cmp_ge_u32_e32 vcc, v1, v0
	s_orn2_b64 s[42:43], vcc, exec
	s_branch .LBB0_573
